# v119 stack plus: barrier after phase 0 is the XCD-hierarchical barrier (was cooperative-groups grid sync)
# speedup vs baseline: 1.0096x; 1.0011x over previous
.LBB0_1362:
	s_waitcnt vmcnt(0)
	s_waitcnt vmcnt(0)
	s_barrier
	s_mov_b64 s[34:35], exec
	v_readlane_b32 s0, v253, 4
	v_readlane_b32 s1, v253, 5
	s_and_b64 s[0:1], s[34:35], s[0:1]
	s_mov_b64 exec, s[0:1]
	s_cbranch_execz .LBB0_1416
	s_add_i32 s22, 0, 0x24000
	v_mov_b32_e32 v0, s22
	s_waitcnt vmcnt(0) expcnt(0) lgkmcnt(0)
	ds_read_b32 v2, v0
	v_readlane_b32 s0, v254, 22
	s_waitcnt lgkmcnt(0)
	v_cmp_ne_u32_e32 vcc, 0, v2
	v_mov_b32_e32 v0, s0
	ds_read_b32 v0, v0
	s_cbranch_vccnz .LBB0_1380
	s_mov_b32 s0, 1
	s_branch .LBB0_1367
